# G1 epilogue fast path (90 instructions: cvt + 16 stores, saddr addressing) for units without K/V/conv side outputs
# speedup vs baseline: 1.0035x; 1.0035x over previous
.LBB0_91:
	s_cmpk_gt_i32 s4, 0xff
	s_cbranch_scc1 .Lep1_slow
	s_and_b32 s5, s4, 7
	s_cmp_lt_i32 s18, 2
	s_cbranch_scc0 .Lep1_chk_kv
	s_cmp_eq_u32 s5, 7
	s_cbranch_scc1 .Lep1_slow
	s_branch .Lep1_fast
.Lep1_chk_kv:
	s_cmp_lt_i32 s18, 6
	s_cbranch_scc1 .Lep1_fast
	s_cmp_ge_u32 s5, 6
	s_cbranch_scc1 .Lep1_slow
.Lep1_fast:
	v_lshl_add_u32 v146, s4, 8, v137
	v_lshl_or_b32 v147, s18, 8, v161
	v_mul_u32_u24_e32 v146, 0x1400, v146
	v_lshl_add_u32 v146, v147, 1, v146
	v_cvt_pk_bf16_f32 v148, v124, v125
	v_cvt_pk_bf16_f32 v149, v126, v127
	v_cvt_pk_bf16_f32 v150, v120, v121
	v_cvt_pk_bf16_f32 v151, v122, v123
	global_store_dwordx4 v146, v[148:151], s[16:17]
	v_cvt_pk_bf16_f32 v152, v116, v117
	v_cvt_pk_bf16_f32 v153, v118, v119
	v_cvt_pk_bf16_f32 v154, v112, v113
	v_cvt_pk_bf16_f32 v155, v114, v115
	global_store_dwordx4 v146, v[152:155], s[16:17] offset:256
	v_add_u32_e32 v146, 0x14000, v146
	v_cvt_pk_bf16_f32 v156, v108, v109
	v_cvt_pk_bf16_f32 v157, v110, v111
	v_cvt_pk_bf16_f32 v158, v104, v105
	v_cvt_pk_bf16_f32 v159, v106, v107
	global_store_dwordx4 v146, v[156:159], s[16:17]
	v_cvt_pk_bf16_f32 v148, v100, v101
	v_cvt_pk_bf16_f32 v149, v102, v103
	v_cvt_pk_bf16_f32 v150, v96, v97
	v_cvt_pk_bf16_f32 v151, v98, v99
	global_store_dwordx4 v146, v[148:151], s[16:17] offset:256
	v_add_u32_e32 v146, 0x14000, v146
	v_cvt_pk_bf16_f32 v152, v92, v93
	v_cvt_pk_bf16_f32 v153, v94, v95
	v_cvt_pk_bf16_f32 v154, v88, v89
	v_cvt_pk_bf16_f32 v155, v90, v91
	global_store_dwordx4 v146, v[152:155], s[16:17]
	v_cvt_pk_bf16_f32 v156, v84, v85
	v_cvt_pk_bf16_f32 v157, v86, v87
	v_cvt_pk_bf16_f32 v158, v80, v81
	v_cvt_pk_bf16_f32 v159, v82, v83
	global_store_dwordx4 v146, v[156:159], s[16:17] offset:256
	v_add_u32_e32 v146, 0x14000, v146
	v_cvt_pk_bf16_f32 v148, v76, v77
	v_cvt_pk_bf16_f32 v149, v78, v79
	v_cvt_pk_bf16_f32 v150, v72, v73
	v_cvt_pk_bf16_f32 v151, v74, v75
	global_store_dwordx4 v146, v[148:151], s[16:17]
	v_cvt_pk_bf16_f32 v152, v68, v69
	v_cvt_pk_bf16_f32 v153, v70, v71
	v_cvt_pk_bf16_f32 v154, v64, v65
	v_cvt_pk_bf16_f32 v155, v66, v67
	global_store_dwordx4 v146, v[152:155], s[16:17] offset:256
	v_add_u32_e32 v146, 0x64000, v146
	v_cvt_pk_bf16_f32 v156, v60, v61
	v_cvt_pk_bf16_f32 v157, v62, v63
	v_cvt_pk_bf16_f32 v158, v56, v57
	v_cvt_pk_bf16_f32 v159, v58, v59
	global_store_dwordx4 v146, v[156:159], s[16:17]
	v_cvt_pk_bf16_f32 v148, v52, v53
	v_cvt_pk_bf16_f32 v149, v54, v55
	v_cvt_pk_bf16_f32 v150, v48, v49
	v_cvt_pk_bf16_f32 v151, v50, v51
	global_store_dwordx4 v146, v[148:151], s[16:17] offset:256
	v_add_u32_e32 v146, 0x14000, v146
	v_cvt_pk_bf16_f32 v152, v44, v45
	v_cvt_pk_bf16_f32 v153, v46, v47
	v_cvt_pk_bf16_f32 v154, v40, v41
	v_cvt_pk_bf16_f32 v155, v42, v43
	global_store_dwordx4 v146, v[152:155], s[16:17]
	v_cvt_pk_bf16_f32 v156, v36, v37
	v_cvt_pk_bf16_f32 v157, v38, v39
	v_cvt_pk_bf16_f32 v158, v32, v33
	v_cvt_pk_bf16_f32 v159, v34, v35
	global_store_dwordx4 v146, v[156:159], s[16:17] offset:256
	v_add_u32_e32 v146, 0x14000, v146
	v_cvt_pk_bf16_f32 v148, v28, v29
	v_cvt_pk_bf16_f32 v149, v30, v31
	v_cvt_pk_bf16_f32 v150, v24, v25
	v_cvt_pk_bf16_f32 v151, v26, v27
	global_store_dwordx4 v146, v[148:151], s[16:17]
	v_cvt_pk_bf16_f32 v152, v20, v21
	v_cvt_pk_bf16_f32 v153, v22, v23
	v_cvt_pk_bf16_f32 v154, v16, v17
	v_cvt_pk_bf16_f32 v155, v18, v19
	global_store_dwordx4 v146, v[152:155], s[16:17] offset:256
	v_add_u32_e32 v146, 0x14000, v146
	v_cvt_pk_bf16_f32 v156, v12, v13
	v_cvt_pk_bf16_f32 v157, v14, v15
	v_cvt_pk_bf16_f32 v158, v8, v9
	v_cvt_pk_bf16_f32 v159, v10, v11
	global_store_dwordx4 v146, v[156:159], s[16:17]
	v_cvt_pk_bf16_f32 v148, v4, v5
	v_cvt_pk_bf16_f32 v149, v6, v7
	v_cvt_pk_bf16_f32 v150, v0, v1
	v_cvt_pk_bf16_f32 v151, v2, v3
	global_store_dwordx4 v146, v[148:151], s[16:17] offset:256
	v_readlane_b32 s53, v249, 0
	s_branch .Lep1_join

.LBB0_243:
	s_or_b64 exec, exec, s[8:9]
.Lep1_join:
	s_andn2_b64 vcc, exec, s[2:3]
	s_mov_b64 s[2:3], -1
	s_cbranch_vccnz .LBB0_80
.LBB0_244:
	s_andn2_b64 vcc, exec, s[14:15]
	s_cbranch_vccnz .LBB0_79
	s_barrier
	s_branch .LBB0_79
